# attention softmax: PV MFMAs slipped earlier in each group (positions 2 and 9)
# baseline (speedup 1.0000x reference)
.Latt_nogate:
	v_exp_f32_e32 v114, v114
	v_exp_f32_e32 v115, v115
	v_exp_f32_e32 v116, v116
	v_exp_f32_e32 v117, v117
	v_exp_f32_e32 v118, v118
	v_exp_f32_e32 v119, v119
	v_exp_f32_e32 v120, v120
	v_exp_f32_e32 v121, v121
	v_cvt_pk_bf16_f32 v66, v114, v115
	v_cvt_pk_bf16_f32 v67, v116, v117
	v_cvt_pk_bf16_f32 v68, v118, v119
	v_cvt_pk_bf16_f32 v69, v120, v121
	v_add_f32_e32 v178, v114, v115
	v_add_f32_e32 v179, v116, v117
	v_add_f32_e32 v180, v118, v119
	v_add_f32_e32 v181, v120, v121
	v_add_f32_e32 v178, v178, v179
	v_add_f32_e32 v180, v180, v181
	v_add_f32_e32 v178, v178, v180
	v_add_f32_e32 v210, v210, v178
	ds_read_b64_tr_b16 v[240:241], v185 offset:56320
	ds_read_b64_tr_b16 v[242:243], v185 offset:56832
	ds_read_b64_tr_b16 v[244:245], v185 offset:60416
	s_waitcnt lgkmcnt(11)
	ds_read_b64_tr_b16 v[246:247], v185 offset:60928
	ds_read_b64_tr_b16 v[114:115], v184 offset:53248
	ds_read_b64_tr_b16 v[116:117], v184 offset:53760
	ds_read_b64_tr_b16 v[118:119], v184 offset:57344
	s_waitcnt lgkmcnt(11)
	ds_read_b64_tr_b16 v[120:121], v184 offset:57856
	v_exp_f32_e32 v122, v122
	v_exp_f32_e32 v123, v123
	v_mfma_f32_32x32x16_bf16 v[34:49], v[66:69], v[216:219], v[34:49]
	v_exp_f32_e32 v124, v124
	v_exp_f32_e32 v125, v125
	v_exp_f32_e32 v126, v126
	v_exp_f32_e32 v127, v127
	v_exp_f32_e32 v128, v128
	v_exp_f32_e32 v129, v129
	v_cvt_pk_bf16_f32 v70, v122, v123
	v_mfma_f32_32x32x16_bf16 v[50:65], v[66:69], v[220:223], v[50:65]
	v_cvt_pk_bf16_f32 v71, v124, v125
	v_cvt_pk_bf16_f32 v72, v126, v127
	v_cvt_pk_bf16_f32 v73, v128, v129
	v_add_f32_e32 v178, v122, v123
	v_add_f32_e32 v179, v124, v125
	v_add_f32_e32 v180, v126, v127
	v_add_f32_e32 v181, v128, v129
	v_add_f32_e32 v178, v178, v179
	v_add_f32_e32 v180, v180, v181
	v_add_f32_e32 v178, v178, v180
	v_add_f32_e32 v210, v210, v178
	ds_read_b64_tr_b16 v[122:123], v184 offset:54272
	ds_read_b64_tr_b16 v[124:125], v184 offset:54784
	ds_read_b64_tr_b16 v[126:127], v184 offset:58368
	s_waitcnt lgkmcnt(11)
	ds_read_b64_tr_b16 v[128:129], v184 offset:58880
	v_exp_f32_e32 v98, v98
	v_exp_f32_e32 v99, v99
	v_mfma_f32_32x32x16_bf16 v[34:49], v[70:73], v[224:227], v[34:49]
	v_exp_f32_e32 v100, v100
	v_exp_f32_e32 v101, v101
	v_exp_f32_e32 v102, v102
	v_exp_f32_e32 v103, v103
	v_exp_f32_e32 v104, v104
	v_exp_f32_e32 v105, v105
	v_cvt_pk_bf16_f32 v74, v98, v99
	v_mfma_f32_32x32x16_bf16 v[50:65], v[70:73], v[228:231], v[50:65]
	v_cvt_pk_bf16_f32 v75, v100, v101
	v_cvt_pk_bf16_f32 v76, v102, v103
	v_cvt_pk_bf16_f32 v77, v104, v105
	v_add_f32_e32 v178, v98, v99
	v_add_f32_e32 v179, v100, v101
	v_add_f32_e32 v180, v102, v103
	v_add_f32_e32 v181, v104, v105
	v_add_f32_e32 v178, v178, v179
	v_add_f32_e32 v180, v180, v181
	v_add_f32_e32 v178, v178, v180
	v_add_f32_e32 v210, v210, v178
	ds_read_b64_tr_b16 v[98:99], v184 offset:55296
	ds_read_b64_tr_b16 v[100:101], v184 offset:55808
	ds_read_b64_tr_b16 v[102:103], v184 offset:59392
	s_waitcnt lgkmcnt(11)
	ds_read_b64_tr_b16 v[104:105], v184 offset:59904
	v_exp_f32_e32 v106, v106
	v_exp_f32_e32 v107, v107
	v_mfma_f32_32x32x16_bf16 v[34:49], v[74:77], v[232:235], v[34:49]
	v_exp_f32_e32 v108, v108
	v_exp_f32_e32 v109, v109
	v_exp_f32_e32 v110, v110
	v_exp_f32_e32 v111, v111
	v_exp_f32_e32 v112, v112
	v_exp_f32_e32 v113, v113
	v_cvt_pk_bf16_f32 v78, v106, v107
	v_mfma_f32_32x32x16_bf16 v[50:65], v[74:77], v[236:239], v[50:65]
	v_cvt_pk_bf16_f32 v79, v108, v109
	v_cvt_pk_bf16_f32 v80, v110, v111
	v_cvt_pk_bf16_f32 v81, v112, v113
	v_add_f32_e32 v178, v106, v107
	v_add_f32_e32 v179, v108, v109
	v_add_f32_e32 v180, v110, v111
	v_add_f32_e32 v181, v112, v113
	v_add_f32_e32 v178, v178, v179
	v_add_f32_e32 v180, v180, v181
	v_add_f32_e32 v178, v178, v180
	v_add_f32_e32 v210, v210, v178
	ds_read_b64_tr_b16 v[106:107], v184 offset:56320
	ds_read_b64_tr_b16 v[108:109], v184 offset:56832
	ds_read_b64_tr_b16 v[110:111], v184 offset:60416
	s_waitcnt lgkmcnt(11)
	ds_read_b64_tr_b16 v[112:113], v184 offset:60928
	v_exp_f32_e32 v2, v2
	v_exp_f32_e32 v3, v3
	v_mfma_f32_32x32x16_bf16 v[34:49], v[78:81], v[240:243], v[34:49]
	v_exp_f32_e32 v4, v4
	v_exp_f32_e32 v5, v5
	v_exp_f32_e32 v6, v6
	v_exp_f32_e32 v7, v7
	v_exp_f32_e32 v8, v8
	v_exp_f32_e32 v9, v9
	v_cvt_pk_bf16_f32 v66, v2, v3
	v_mfma_f32_32x32x16_bf16 v[50:65], v[78:81], v[244:247], v[50:65]
	v_cvt_pk_bf16_f32 v67, v4, v5
	v_cvt_pk_bf16_f32 v68, v6, v7
	v_cvt_pk_bf16_f32 v69, v8, v9
	v_add_f32_e32 v178, v2, v3
	v_add_f32_e32 v179, v4, v5
	v_add_f32_e32 v180, v6, v7
	v_add_f32_e32 v181, v8, v9
	v_add_f32_e32 v178, v178, v179
	v_add_f32_e32 v180, v180, v181
	v_add_f32_e32 v178, v178, v180
	v_add_f32_e32 v210, v210, v178
	v_exp_f32_e32 v10, v10
	v_exp_f32_e32 v11, v11
	v_mfma_f32_32x32x16_bf16 v[34:49], v[66:69], v[114:117], v[34:49]
	v_exp_f32_e32 v12, v12
	v_exp_f32_e32 v13, v13
	v_exp_f32_e32 v14, v14
	v_exp_f32_e32 v15, v15
	v_exp_f32_e32 v16, v16
	v_exp_f32_e32 v17, v17
	v_cvt_pk_bf16_f32 v70, v10, v11
	v_mfma_f32_32x32x16_bf16 v[50:65], v[66:69], v[118:121], v[50:65]
	v_cvt_pk_bf16_f32 v71, v12, v13
	v_cvt_pk_bf16_f32 v72, v14, v15
	v_cvt_pk_bf16_f32 v73, v16, v17
	v_add_f32_e32 v178, v10, v11
	v_add_f32_e32 v179, v12, v13
	v_add_f32_e32 v180, v14, v15
	v_add_f32_e32 v181, v16, v17
	v_add_f32_e32 v178, v178, v179
	v_add_f32_e32 v180, v180, v181
	v_add_f32_e32 v178, v178, v180
	v_add_f32_e32 v210, v210, v178
	v_exp_f32_e32 v18, v18
	v_exp_f32_e32 v19, v19
	s_waitcnt lgkmcnt(10)
	v_mfma_f32_32x32x16_bf16 v[34:49], v[70:73], v[122:125], v[34:49]
	v_exp_f32_e32 v20, v20
	v_exp_f32_e32 v21, v21
	v_exp_f32_e32 v22, v22
	v_exp_f32_e32 v23, v23
	v_exp_f32_e32 v24, v24
	v_exp_f32_e32 v25, v25
	v_cvt_pk_bf16_f32 v74, v18, v19
	s_waitcnt lgkmcnt(8)
	v_mfma_f32_32x32x16_bf16 v[50:65], v[70:73], v[126:129], v[50:65]
	v_cvt_pk_bf16_f32 v75, v20, v21
	v_cvt_pk_bf16_f32 v76, v22, v23
	v_cvt_pk_bf16_f32 v77, v24, v25
	v_add_f32_e32 v178, v18, v19
	v_add_f32_e32 v179, v20, v21
	v_add_f32_e32 v180, v22, v23
	v_add_f32_e32 v181, v24, v25
	v_add_f32_e32 v178, v178, v179
	v_add_f32_e32 v180, v180, v181
	v_add_f32_e32 v178, v178, v180
	v_add_f32_e32 v210, v210, v178
	v_exp_f32_e32 v26, v26
	v_exp_f32_e32 v27, v27
	s_waitcnt lgkmcnt(6)
	v_mfma_f32_32x32x16_bf16 v[34:49], v[74:77], v[98:101], v[34:49]
	v_exp_f32_e32 v28, v28
	v_exp_f32_e32 v29, v29
	v_exp_f32_e32 v30, v30
	v_exp_f32_e32 v31, v31
	v_exp_f32_e32 v32, v32
	v_exp_f32_e32 v33, v33
	v_cvt_pk_bf16_f32 v78, v26, v27
	s_waitcnt lgkmcnt(4)
	v_mfma_f32_32x32x16_bf16 v[50:65], v[74:77], v[102:105], v[50:65]
	v_cvt_pk_bf16_f32 v79, v28, v29
	v_cvt_pk_bf16_f32 v80, v30, v31
	v_cvt_pk_bf16_f32 v81, v32, v33
	v_add_f32_e32 v178, v26, v27
	v_add_f32_e32 v179, v28, v29
	v_add_f32_e32 v180, v30, v31
	v_add_f32_e32 v181, v32, v33
	v_add_f32_e32 v178, v178, v179
	v_add_f32_e32 v180, v180, v181
	v_add_f32_e32 v178, v178, v180
	v_add_f32_e32 v210, v210, v178
	s_waitcnt lgkmcnt(2)
	v_mfma_f32_32x32x16_bf16 v[34:49], v[78:81], v[106:109], v[34:49]
	s_waitcnt lgkmcnt(0)
	v_mfma_f32_32x32x16_bf16 v[50:65], v[78:81], v[110:113], v[50:65]
	s_cmp_eq_u32 s35, 0
	s_cbranch_scc1 .Latt_rs
	v_cmp_lt_f32_e32 vcc, 0x4b800000, v210
	s_cbranch_vccnz .Latt_rs
